# ctx_finish row loop issues all slab/residual/gain loads before one wait (on top of OUTPROJ ctx-tile deferral + MLP1 rebalance)
# speedup vs baseline: 1.0542x; 1.0024x over previous
; __device__ __forceinline__ unsigned pk2(float lo, float hi) { f32x2v v = {lo, hi}; bf16x2v b = __builtin_convertvector(v, bf16x2v); return __builtin_bit_cast(unsigned, b); }
; __device__ __forceinline__ void ctx_finish_phase(const Params& p, int tid) {
;     ...
;     for (int row = blockIdx.x * 8 + wave; row < MC; row += gridDim.x * 8) {
;         float ss = 0.f;
; #pragma unroll
;         for (int j = 0; j < 4; ++j) {
;             const int col = 4 * lane + 256 * j; const size_t o = (size_t)row * DM + col;
;             f32x4 a = *(const f32x4*)(SL + o);
; #pragma unroll
;             for (int ks = 1; ks < 4; ++ks) a += *(const f32x4*)(SL + (size_t)ks * MC * DM + o);
;             const f32x4 x = *(const f32x4*)(XC + o) + *(const f32x4*)(gate + col) * a;
;             *(f32x4*)(XC + o) = x;
;             ss += (x[0] * x[0] + x[1] * x[1]) + (x[2] * x[2] + x[3] * x[3]);
;             const f32x4 y = x * *(const f32x4*)(gs + col);
;             *(u32x2*)(A1 + (size_t)(MX + row) * DM + col) = (u32x2){pk2(y[0], y[1]), pk2(y[2], y[3])};
;         }
;         ss = wave_sum(ss);
;         if (lane == 0) RS1[MX + row] = ss;
;     }
.LBB0_816:
	v_ashrrev_i32_e32 v1, 31, v0
	v_lshlrev_b64 v[30:31], 10, v[0:1]
	v_readlane_b32 s10, v255, 11
	v_readlane_b32 s11, v255, 12
	v_readlane_b32 s8, v252, 25
	v_readlane_b32 s9, v252, 26
	s_mov_b32 s2, 0x1000000
	s_mov_b32 s12, 0x1800000
	v_add_u32_e32 v28, 0x8000, v0
	v_ashrrev_i32_e32 v29, 31, v28
	v_lshlrev_b64 v[28:29], 11, v[28:29]
	v_lshl_add_u64 v[28:29], v[26:27], 0, v[28:29]
	v_or_b32_e32 v34, v30, v2
	v_mov_b32_e32 v35, v31
	v_lshlrev_b64 v[36:37], 2, v[34:35]
	v_lshl_add_u64 v[44:45], s[10:11], 0, v[36:37]
	global_load_dwordx4 v[48:51], v[44:45], off
	v_add_co_u32_e32 v46, vcc, s16, v44
	s_nop 1
	v_addc_co_u32_e32 v47, vcc, 0, v45, vcc
	global_load_dwordx4 v[52:55], v[46:47], off
	v_add_co_u32_e32 v46, vcc, s2, v44
	s_nop 1
	v_addc_co_u32_e32 v47, vcc, 0, v45, vcc
	global_load_dwordx4 v[56:59], v[46:47], off
	v_add_co_u32_e32 v46, vcc, s12, v44
	s_nop 1
	v_addc_co_u32_e32 v47, vcc, 0, v45, vcc
	global_load_dwordx4 v[60:63], v[46:47], off
	v_lshl_add_u64 v[36:37], s[8:9], 0, v[36:37]
	global_load_dwordx4 v[64:67], v[36:37], off
	global_load_dwordx4 v[68:71], v[4:5], off
	global_load_dwordx4 v[72:75], v[6:7], off
	v_or_b32_e32 v34, v30, v8
	v_mov_b32_e32 v35, v31
	v_lshlrev_b64 v[38:39], 2, v[34:35]
	v_lshl_add_u64 v[44:45], s[10:11], 0, v[38:39]
	global_load_dwordx4 v[76:79], v[44:45], off
	v_add_co_u32_e32 v46, vcc, s16, v44
	s_nop 1
	v_addc_co_u32_e32 v47, vcc, 0, v45, vcc
	global_load_dwordx4 v[80:83], v[46:47], off
	v_add_co_u32_e32 v46, vcc, s2, v44
	s_nop 1
	v_addc_co_u32_e32 v47, vcc, 0, v45, vcc
	global_load_dwordx4 v[84:87], v[46:47], off
	v_add_co_u32_e32 v46, vcc, s12, v44
	s_nop 1
	v_addc_co_u32_e32 v47, vcc, 0, v45, vcc
	global_load_dwordx4 v[88:91], v[46:47], off
	v_lshl_add_u64 v[38:39], s[8:9], 0, v[38:39]
	global_load_dwordx4 v[92:95], v[38:39], off
	global_load_dwordx4 v[96:99], v[10:11], off
	global_load_dwordx4 v[100:103], v[12:13], off
	v_or_b32_e32 v34, v30, v14
	v_mov_b32_e32 v35, v31
	v_lshlrev_b64 v[40:41], 2, v[34:35]
	v_lshl_add_u64 v[44:45], s[10:11], 0, v[40:41]
	global_load_dwordx4 v[104:107], v[44:45], off
	v_add_co_u32_e32 v46, vcc, s16, v44
	s_nop 1
	v_addc_co_u32_e32 v47, vcc, 0, v45, vcc
	global_load_dwordx4 v[108:111], v[46:47], off
	v_add_co_u32_e32 v46, vcc, s2, v44
	s_nop 1
	v_addc_co_u32_e32 v47, vcc, 0, v45, vcc
	global_load_dwordx4 v[112:115], v[46:47], off
	v_add_co_u32_e32 v46, vcc, s12, v44
	s_nop 1
	v_addc_co_u32_e32 v47, vcc, 0, v45, vcc
	global_load_dwordx4 v[116:119], v[46:47], off
	v_lshl_add_u64 v[40:41], s[8:9], 0, v[40:41]
	global_load_dwordx4 v[120:123], v[40:41], off
	global_load_dwordx4 v[124:127], v[16:17], off
	global_load_dwordx4 v[128:131], v[18:19], off
	v_or_b32_e32 v34, v30, v20
	v_mov_b32_e32 v35, v31
	v_lshlrev_b64 v[42:43], 2, v[34:35]
	v_lshl_add_u64 v[44:45], s[10:11], 0, v[42:43]
	global_load_dwordx4 v[146:149], v[44:45], off
	v_add_co_u32_e32 v46, vcc, s16, v44
	s_nop 1
	v_addc_co_u32_e32 v47, vcc, 0, v45, vcc
	global_load_dwordx4 v[150:153], v[46:47], off
	v_add_co_u32_e32 v46, vcc, s2, v44
	s_nop 1
	v_addc_co_u32_e32 v47, vcc, 0, v45, vcc
	global_load_dwordx4 v[154:157], v[46:47], off
	v_add_co_u32_e32 v46, vcc, s12, v44
	s_nop 1
	v_addc_co_u32_e32 v47, vcc, 0, v45, vcc
	global_load_dwordx4 v[158:161], v[46:47], off
	v_lshl_add_u64 v[42:43], s[8:9], 0, v[42:43]
	global_load_dwordx4 v[162:165], v[42:43], off
	global_load_dwordx4 v[166:169], v[22:23], off
	global_load_dwordx4 v[170:173], v[24:25], off
	s_waitcnt vmcnt(0)
; __device__ __forceinline__ unsigned pk2(float lo, float hi) { f32x2v v = {lo, hi}; bf16x2v b = __builtin_convertvector(v, bf16x2v); return __builtin_bit_cast(unsigned, b); }
; __device__ __forceinline__ void ctx_finish_phase(const Params& p, int tid) {
;     ...
;     for (int row = blockIdx.x * 8 + wave; row < MC; row += gridDim.x * 8) {
;         float ss = 0.f;
; #pragma unroll
;         for (int j = 0; j < 4; ++j) {
;             const int col = 4 * lane + 256 * j; const size_t o = (size_t)row * DM + col;
;             f32x4 a = *(const f32x4*)(SL + o);
; #pragma unroll
;             for (int ks = 1; ks < 4; ++ks) a += *(const f32x4*)(SL + (size_t)ks * MC * DM + o);
;             const f32x4 x = *(const f32x4*)(XC + o) + *(const f32x4*)(gate + col) * a;
;             *(f32x4*)(XC + o) = x;
;             ss += (x[0] * x[0] + x[1] * x[1]) + (x[2] * x[2] + x[3] * x[3]);
;             const f32x4 y = x * *(const f32x4*)(gs + col);
;             *(u32x2*)(A1 + (size_t)(MX + row) * DM + col) = (u32x2){pk2(y[0], y[1]), pk2(y[2], y[3])};
;         }
;         ss = wave_sum(ss);
;         if (lane == 0) RS1[MX + row] = ss;
;     }
	v_pk_add_f32 v[48:49], v[48:49], v[52:53]
	v_pk_add_f32 v[50:51], v[50:51], v[54:55]
	v_pk_add_f32 v[48:49], v[48:49], v[56:57]
	v_pk_add_f32 v[50:51], v[50:51], v[58:59]
	v_pk_add_f32 v[48:49], v[48:49], v[60:61]
	v_pk_add_f32 v[50:51], v[50:51], v[62:63]
	v_pk_fma_f32 v[64:65], v[48:49], v[68:69], v[64:65]
	v_pk_fma_f32 v[66:67], v[50:51], v[70:71], v[66:67]
	global_store_dwordx4 v[36:37], v[64:67], off
	v_mul_f32_e32 v34, v65, v65
	v_mul_f32_e32 v35, v67, v67
	v_fmac_f32_e32 v34, v64, v64
	v_fmac_f32_e32 v35, v66, v66
	v_add_f32_e32 v47, v34, v35
	v_pk_mul_f32 v[48:49], v[64:65], v[72:73]
	v_pk_mul_f32 v[50:51], v[66:67], v[74:75]
	s_nop 0
	v_cvt_pk_bf16_f32 v48, v48, v49
	v_cvt_pk_bf16_f32 v49, v50, v51
	global_store_dwordx2 v[28:29], v[48:49], off
	v_pk_add_f32 v[76:77], v[76:77], v[80:81]
	v_pk_add_f32 v[78:79], v[78:79], v[82:83]
	v_pk_add_f32 v[76:77], v[76:77], v[84:85]
	v_pk_add_f32 v[78:79], v[78:79], v[86:87]
	v_pk_add_f32 v[76:77], v[76:77], v[88:89]
	v_pk_add_f32 v[78:79], v[78:79], v[90:91]
	v_pk_fma_f32 v[92:93], v[76:77], v[96:97], v[92:93]
	v_pk_fma_f32 v[94:95], v[78:79], v[98:99], v[94:95]
	global_store_dwordx4 v[38:39], v[92:95], off
	v_mul_f32_e32 v34, v93, v93
	v_mul_f32_e32 v35, v95, v95
	v_fmac_f32_e32 v34, v92, v92
	v_fmac_f32_e32 v35, v94, v94
	v_add_f32_e32 v34, v34, v35
	v_add_f32_e32 v47, v47, v34
	v_pk_mul_f32 v[76:77], v[92:93], v[100:101]
	v_pk_mul_f32 v[78:79], v[94:95], v[102:103]
	s_nop 0
	v_cvt_pk_bf16_f32 v76, v76, v77
	v_cvt_pk_bf16_f32 v77, v78, v79
	global_store_dwordx2 v[28:29], v[76:77], off offset:512
	v_pk_add_f32 v[104:105], v[104:105], v[108:109]
	v_pk_add_f32 v[106:107], v[106:107], v[110:111]
	v_pk_add_f32 v[104:105], v[104:105], v[112:113]
	v_pk_add_f32 v[106:107], v[106:107], v[114:115]
	v_pk_add_f32 v[104:105], v[104:105], v[116:117]
	v_pk_add_f32 v[106:107], v[106:107], v[118:119]
	v_pk_fma_f32 v[120:121], v[104:105], v[124:125], v[120:121]
	v_pk_fma_f32 v[122:123], v[106:107], v[126:127], v[122:123]
	global_store_dwordx4 v[40:41], v[120:123], off
	v_mul_f32_e32 v34, v121, v121
	v_mul_f32_e32 v35, v123, v123
	v_fmac_f32_e32 v34, v120, v120
	v_fmac_f32_e32 v35, v122, v122
	v_add_f32_e32 v34, v34, v35
	v_add_f32_e32 v47, v47, v34
	v_pk_mul_f32 v[104:105], v[120:121], v[128:129]
	v_pk_mul_f32 v[106:107], v[122:123], v[130:131]
	s_nop 0
	v_cvt_pk_bf16_f32 v104, v104, v105
	v_cvt_pk_bf16_f32 v105, v106, v107
	global_store_dwordx2 v[28:29], v[104:105], off offset:1024
	v_pk_add_f32 v[146:147], v[146:147], v[150:151]
	v_pk_add_f32 v[148:149], v[148:149], v[152:153]
	v_pk_add_f32 v[146:147], v[146:147], v[154:155]
	v_pk_add_f32 v[148:149], v[148:149], v[156:157]
	v_pk_add_f32 v[146:147], v[146:147], v[158:159]
	v_pk_add_f32 v[148:149], v[148:149], v[160:161]
	v_pk_fma_f32 v[162:163], v[146:147], v[166:167], v[162:163]
	v_pk_fma_f32 v[164:165], v[148:149], v[168:169], v[164:165]
	global_store_dwordx4 v[42:43], v[162:165], off
	v_mul_f32_e32 v34, v163, v163
	v_mul_f32_e32 v35, v165, v165
	v_fmac_f32_e32 v34, v162, v162
	v_fmac_f32_e32 v35, v164, v164
	v_add_f32_e32 v34, v34, v35
	v_add_f32_e32 v47, v47, v34
	v_pk_mul_f32 v[146:147], v[162:163], v[170:171]
	v_pk_mul_f32 v[148:149], v[164:165], v[172:173]
	s_nop 0
	v_cvt_pk_bf16_f32 v146, v146, v147
	v_cvt_pk_bf16_f32 v147, v148, v149
	global_store_dwordx2 v[28:29], v[146:147], off offset:1536
	v_mov_b32_e32 v42, v47
	ds_bpermute_b32 v28, v3, v42
	s_waitcnt lgkmcnt(0)
	v_add_f32_e32 v28, v42, v28
	ds_bpermute_b32 v29, v9, v28
	s_waitcnt lgkmcnt(0)
	v_add_f32_e32 v28, v28, v29
	ds_bpermute_b32 v29, v15, v28
	s_waitcnt lgkmcnt(0)
	v_add_f32_e32 v28, v28, v29
	ds_bpermute_b32 v29, v21, v28
	s_waitcnt lgkmcnt(0)
	v_add_f32_e32 v28, v28, v29
	ds_bpermute_b32 v29, v32, v28
	s_waitcnt lgkmcnt(0)
	v_add_f32_e32 v28, v28, v29
	ds_bpermute_b32 v29, v33, v28
	s_and_saveexec_b64 s[8:9], s[0:1]
	s_cbranch_execz .LBB0_815
	s_waitcnt lgkmcnt(0)
	v_add_f32_e32 v30, v28, v29
	v_lshl_add_u64 v[28:29], v[0:1], 2, s[88:89]
	v_add_co_u32_e32 v28, vcc, 0x3742000, v28
	s_nop 1
	v_addc_co_u32_e32 v29, vcc, 0, v29, vcc
	global_store_dword v[28:29], v30, off
	s_branch .LBB0_815
